# s5 pass C: B*u products of each 32-step half on f32 matrix cores (v_mfma_f32_32x32x2_f32), step code keeps rotation + bf16 image writes
# baseline (speedup 1.0000x reference)
.LBB0_880:
	v_and_b32_e32 v252, 31, v226
	v_and_b32_e32 v138, 32, v226
	v_lshlrev_b32_e32 v252, 6, v252
	v_add3_u32 v252, v252, v138, v110
	v_add_u32_e32 v252, 0x11000, v252
	ds_read_b128 v[130:133], v252
	ds_read_b128 v[134:137], v252 offset:16
	s_nop 1
	v_permlane32_swap_b32_e32 v54, v72
	v_permlane32_swap_b32_e32 v55, v73
	v_permlane32_swap_b32_e32 v56, v74
	v_permlane32_swap_b32_e32 v57, v75
	v_permlane32_swap_b32_e32 v58, v76
	v_permlane32_swap_b32_e32 v59, v77
	v_permlane32_swap_b32_e32 v60, v78
	v_permlane32_swap_b32_e32 v61, v79
	v_permlane32_swap_b32_e32 v62, v80
	v_permlane32_swap_b32_e32 v63, v81
	v_permlane32_swap_b32_e32 v64, v82
	v_permlane32_swap_b32_e32 v65, v83
	v_permlane32_swap_b32_e32 v68, v84
	v_permlane32_swap_b32_e32 v69, v85
	v_permlane32_swap_b32_e32 v70, v86
	v_permlane32_swap_b32_e32 v71, v87
	v_sub_f32_e32 v139, 0, v52
	s_waitcnt lgkmcnt(0)
	s_nop 1
	v_mfma_f32_32x32x2_f32 v[176:191], v130, v54, 0
	v_mfma_f32_32x32x2_f32 v[192:207], v130, v72, 0
	v_mfma_f32_32x32x2_f32 v[208:223], v130, v55, 0
	v_mfma_f32_32x32x2_f32 v[144:159], v130, v73, 0
	v_mfma_f32_32x32x2_f32 v[176:191], v131, v56, v[176:191]
	v_mfma_f32_32x32x2_f32 v[192:207], v131, v74, v[192:207]
	v_mfma_f32_32x32x2_f32 v[208:223], v131, v57, v[208:223]
	v_mfma_f32_32x32x2_f32 v[144:159], v131, v75, v[144:159]
	v_mfma_f32_32x32x2_f32 v[176:191], v132, v58, v[176:191]
	v_mfma_f32_32x32x2_f32 v[192:207], v132, v76, v[192:207]
	v_mfma_f32_32x32x2_f32 v[208:223], v132, v59, v[208:223]
	v_mfma_f32_32x32x2_f32 v[144:159], v132, v77, v[144:159]
	v_mfma_f32_32x32x2_f32 v[176:191], v133, v60, v[176:191]
	v_mfma_f32_32x32x2_f32 v[192:207], v133, v78, v[192:207]
	v_mfma_f32_32x32x2_f32 v[208:223], v133, v61, v[208:223]
	v_mfma_f32_32x32x2_f32 v[144:159], v133, v79, v[144:159]
	v_mfma_f32_32x32x2_f32 v[176:191], v134, v62, v[176:191]
	v_mfma_f32_32x32x2_f32 v[192:207], v134, v80, v[192:207]
	v_mfma_f32_32x32x2_f32 v[208:223], v134, v63, v[208:223]
	v_mfma_f32_32x32x2_f32 v[144:159], v134, v81, v[144:159]
	v_mfma_f32_32x32x2_f32 v[176:191], v135, v64, v[176:191]
	v_mfma_f32_32x32x2_f32 v[192:207], v135, v82, v[192:207]
	v_mfma_f32_32x32x2_f32 v[208:223], v135, v65, v[208:223]
	v_mfma_f32_32x32x2_f32 v[144:159], v135, v83, v[144:159]
	v_mfma_f32_32x32x2_f32 v[176:191], v136, v68, v[176:191]
	v_mfma_f32_32x32x2_f32 v[192:207], v136, v84, v[192:207]
	v_mfma_f32_32x32x2_f32 v[208:223], v136, v69, v[208:223]
	v_mfma_f32_32x32x2_f32 v[144:159], v136, v85, v[144:159]
	v_mfma_f32_32x32x2_f32 v[176:191], v137, v70, v[176:191]
	v_mfma_f32_32x32x2_f32 v[192:207], v137, v86, v[192:207]
	v_mfma_f32_32x32x2_f32 v[208:223], v137, v71, v[208:223]
	v_mfma_f32_32x32x2_f32 v[144:159], v137, v87, v[144:159]
	s_nop 7
	s_nop 7
	s_nop 3
	v_permlane32_swap_b32_e32 v176, v192
	v_permlane32_swap_b32_e32 v208, v144
	v_permlane32_swap_b32_e32 v177, v193
	v_permlane32_swap_b32_e32 v209, v145
	v_permlane32_swap_b32_e32 v178, v194
	v_permlane32_swap_b32_e32 v210, v146
	v_permlane32_swap_b32_e32 v179, v195
	v_permlane32_swap_b32_e32 v211, v147
	v_permlane32_swap_b32_e32 v180, v196
	v_permlane32_swap_b32_e32 v212, v148
	v_permlane32_swap_b32_e32 v181, v197
	v_permlane32_swap_b32_e32 v213, v149
	v_permlane32_swap_b32_e32 v182, v198
	v_permlane32_swap_b32_e32 v214, v150
	v_permlane32_swap_b32_e32 v183, v199
	v_permlane32_swap_b32_e32 v215, v151
	v_permlane32_swap_b32_e32 v184, v200
	v_permlane32_swap_b32_e32 v216, v152
	v_permlane32_swap_b32_e32 v185, v201
	v_permlane32_swap_b32_e32 v217, v153
	v_permlane32_swap_b32_e32 v186, v202
	v_permlane32_swap_b32_e32 v218, v154
	v_permlane32_swap_b32_e32 v187, v203
	v_permlane32_swap_b32_e32 v219, v155
	v_permlane32_swap_b32_e32 v188, v204
	v_permlane32_swap_b32_e32 v220, v156
	v_permlane32_swap_b32_e32 v189, v205
	v_permlane32_swap_b32_e32 v221, v157
	v_permlane32_swap_b32_e32 v190, v206
	v_permlane32_swap_b32_e32 v222, v158
	v_permlane32_swap_b32_e32 v191, v207
	v_permlane32_swap_b32_e32 v223, v159
	s_nop 1
	v_fmac_f32_e32 v176, v88, v66
	v_fmac_f32_e32 v208, v88, v67
	v_fmac_f32_e32 v176, v52, v67
	v_fmac_f32_e32 v208, v139, v66
	v_cvt_pk_bf16_f32 v140, v176, v208
	ds_write_b16_d16_hi v109, v140
	ds_write_b16 v109, v140 offset:128
	v_fmac_f32_e32 v177, v88, v176
	v_fmac_f32_e32 v209, v88, v208
	v_fmac_f32_e32 v177, v52, v208
	v_fmac_f32_e32 v209, v139, v176
	v_cvt_pk_bf16_f32 v141, v177, v209
	ds_write_b16_d16_hi v109, v141 offset:272
	ds_write_b16 v109, v141 offset:400
	v_fmac_f32_e32 v178, v88, v177
	v_fmac_f32_e32 v210, v88, v209
	v_fmac_f32_e32 v178, v52, v209
	v_fmac_f32_e32 v210, v139, v177
	v_cvt_pk_bf16_f32 v140, v178, v210
	ds_write_b16_d16_hi v109, v140 offset:544
	ds_write_b16 v109, v140 offset:672
	v_fmac_f32_e32 v179, v88, v178
	v_fmac_f32_e32 v211, v88, v210
	v_fmac_f32_e32 v179, v52, v210
	v_fmac_f32_e32 v211, v139, v178
	v_cvt_pk_bf16_f32 v141, v179, v211
	ds_write_b16_d16_hi v109, v141 offset:816
	ds_write_b16 v109, v141 offset:944
	s_waitcnt lgkmcnt(4)
	v_fmac_f32_e32 v192, v88, v179
	v_fmac_f32_e32 v144, v88, v211
	v_fmac_f32_e32 v192, v52, v211
	v_fmac_f32_e32 v144, v139, v179
	v_cvt_pk_bf16_f32 v140, v192, v144
	ds_write_b16_d16_hi v109, v140 offset:1088
	ds_write_b16 v109, v140 offset:1216
	v_fmac_f32_e32 v193, v88, v192
	v_fmac_f32_e32 v145, v88, v144
	v_fmac_f32_e32 v193, v52, v144
	v_fmac_f32_e32 v145, v139, v192
	v_cvt_pk_bf16_f32 v141, v193, v145
	ds_write_b16_d16_hi v109, v141 offset:1360
	ds_write_b16 v109, v141 offset:1488
	v_fmac_f32_e32 v194, v88, v193
	v_fmac_f32_e32 v146, v88, v145
	v_fmac_f32_e32 v194, v52, v145
	v_fmac_f32_e32 v146, v139, v193
	v_cvt_pk_bf16_f32 v140, v194, v146
	ds_write_b16_d16_hi v109, v140 offset:1632
	ds_write_b16 v109, v140 offset:1760
	v_fmac_f32_e32 v195, v88, v194
	v_fmac_f32_e32 v147, v88, v146
	v_fmac_f32_e32 v195, v52, v146
	v_fmac_f32_e32 v147, v139, v194
	v_cvt_pk_bf16_f32 v141, v195, v147
	ds_write_b16_d16_hi v109, v141 offset:1904
	ds_write_b16 v109, v141 offset:2032
	s_waitcnt lgkmcnt(4)
	v_fmac_f32_e32 v180, v88, v195
	v_fmac_f32_e32 v212, v88, v147
	v_fmac_f32_e32 v180, v52, v147
	v_fmac_f32_e32 v212, v139, v195
	v_cvt_pk_bf16_f32 v140, v180, v212
	ds_write_b16_d16_hi v109, v140 offset:2176
	ds_write_b16 v109, v140 offset:2304
	v_fmac_f32_e32 v181, v88, v180
	v_fmac_f32_e32 v213, v88, v212
	v_fmac_f32_e32 v181, v52, v212
	v_fmac_f32_e32 v213, v139, v180
	v_cvt_pk_bf16_f32 v141, v181, v213
	ds_write_b16_d16_hi v109, v141 offset:2448
	ds_write_b16 v109, v141 offset:2576
	v_fmac_f32_e32 v182, v88, v181
	v_fmac_f32_e32 v214, v88, v213
	v_fmac_f32_e32 v182, v52, v213
	v_fmac_f32_e32 v214, v139, v181
	v_cvt_pk_bf16_f32 v140, v182, v214
	ds_write_b16_d16_hi v109, v140 offset:2720
	ds_write_b16 v109, v140 offset:2848
	v_fmac_f32_e32 v183, v88, v182
	v_fmac_f32_e32 v215, v88, v214
	v_fmac_f32_e32 v183, v52, v214
	v_fmac_f32_e32 v215, v139, v182
	v_cvt_pk_bf16_f32 v141, v183, v215
	ds_write_b16_d16_hi v109, v141 offset:2992
	ds_write_b16 v109, v141 offset:3120
	s_waitcnt lgkmcnt(4)
	v_fmac_f32_e32 v196, v88, v183
	v_fmac_f32_e32 v148, v88, v215
	v_fmac_f32_e32 v196, v52, v215
	v_fmac_f32_e32 v148, v139, v183
	v_cvt_pk_bf16_f32 v140, v196, v148
	ds_write_b16_d16_hi v109, v140 offset:3264
	ds_write_b16 v109, v140 offset:3392
	v_fmac_f32_e32 v197, v88, v196
	v_fmac_f32_e32 v149, v88, v148
	v_fmac_f32_e32 v197, v52, v148
	v_fmac_f32_e32 v149, v139, v196
	v_cvt_pk_bf16_f32 v141, v197, v149
	ds_write_b16_d16_hi v109, v141 offset:3536
	ds_write_b16 v109, v141 offset:3664
	v_fmac_f32_e32 v198, v88, v197
	v_fmac_f32_e32 v150, v88, v149
	v_fmac_f32_e32 v198, v52, v149
	v_fmac_f32_e32 v150, v139, v197
	v_cvt_pk_bf16_f32 v140, v198, v150
	ds_write_b16_d16_hi v109, v140 offset:3808
	ds_write_b16 v109, v140 offset:3936
	v_fmac_f32_e32 v199, v88, v198
	v_fmac_f32_e32 v151, v88, v150
	v_fmac_f32_e32 v199, v52, v150
	v_fmac_f32_e32 v151, v139, v198
	v_cvt_pk_bf16_f32 v141, v199, v151
	ds_write_b16_d16_hi v109, v141 offset:4080
	ds_write_b16 v109, v141 offset:4208
	s_waitcnt lgkmcnt(4)
	v_fmac_f32_e32 v184, v88, v199
	v_fmac_f32_e32 v216, v88, v151
	v_fmac_f32_e32 v184, v52, v151
	v_fmac_f32_e32 v216, v139, v199
	v_cvt_pk_bf16_f32 v140, v184, v216
	ds_write_b16_d16_hi v109, v140 offset:4352
	ds_write_b16 v109, v140 offset:4480
	v_fmac_f32_e32 v185, v88, v184
	v_fmac_f32_e32 v217, v88, v216
	v_fmac_f32_e32 v185, v52, v216
	v_fmac_f32_e32 v217, v139, v184
	v_cvt_pk_bf16_f32 v141, v185, v217
	ds_write_b16_d16_hi v109, v141 offset:4624
	ds_write_b16 v109, v141 offset:4752
	v_fmac_f32_e32 v186, v88, v185
	v_fmac_f32_e32 v218, v88, v217
	v_fmac_f32_e32 v186, v52, v217
	v_fmac_f32_e32 v218, v139, v185
	v_cvt_pk_bf16_f32 v140, v186, v218
	ds_write_b16_d16_hi v109, v140 offset:4896
	ds_write_b16 v109, v140 offset:5024
	v_fmac_f32_e32 v187, v88, v186
	v_fmac_f32_e32 v219, v88, v218
	v_fmac_f32_e32 v187, v52, v218
	v_fmac_f32_e32 v219, v139, v186
	v_cvt_pk_bf16_f32 v141, v187, v219
	ds_write_b16_d16_hi v109, v141 offset:5168
	ds_write_b16 v109, v141 offset:5296
	s_waitcnt lgkmcnt(4)
	v_fmac_f32_e32 v200, v88, v187
	v_fmac_f32_e32 v152, v88, v219
	v_fmac_f32_e32 v200, v52, v219
	v_fmac_f32_e32 v152, v139, v187
	v_cvt_pk_bf16_f32 v140, v200, v152
	ds_write_b16_d16_hi v109, v140 offset:5440
	ds_write_b16 v109, v140 offset:5568
	v_fmac_f32_e32 v201, v88, v200
	v_fmac_f32_e32 v153, v88, v152
	v_fmac_f32_e32 v201, v52, v152
	v_fmac_f32_e32 v153, v139, v200
	v_cvt_pk_bf16_f32 v141, v201, v153
	ds_write_b16_d16_hi v109, v141 offset:5712
	ds_write_b16 v109, v141 offset:5840
	v_fmac_f32_e32 v202, v88, v201
	v_fmac_f32_e32 v154, v88, v153
	v_fmac_f32_e32 v202, v52, v153
	v_fmac_f32_e32 v154, v139, v201
	v_cvt_pk_bf16_f32 v140, v202, v154
	ds_write_b16_d16_hi v109, v140 offset:5984
	ds_write_b16 v109, v140 offset:6112
	v_fmac_f32_e32 v203, v88, v202
	v_fmac_f32_e32 v155, v88, v154
	v_fmac_f32_e32 v203, v52, v154
	v_fmac_f32_e32 v155, v139, v202
	v_cvt_pk_bf16_f32 v141, v203, v155
	ds_write_b16_d16_hi v109, v141 offset:6256
	ds_write_b16 v109, v141 offset:6384
	s_waitcnt lgkmcnt(4)
	v_fmac_f32_e32 v188, v88, v203
	v_fmac_f32_e32 v220, v88, v155
	v_fmac_f32_e32 v188, v52, v155
	v_fmac_f32_e32 v220, v139, v203
	v_cvt_pk_bf16_f32 v140, v188, v220
	ds_write_b16_d16_hi v109, v140 offset:6528
	ds_write_b16 v109, v140 offset:6656
	v_fmac_f32_e32 v189, v88, v188
	v_fmac_f32_e32 v221, v88, v220
	v_fmac_f32_e32 v189, v52, v220
	v_fmac_f32_e32 v221, v139, v188
	v_cvt_pk_bf16_f32 v141, v189, v221
	ds_write_b16_d16_hi v109, v141 offset:6800
	ds_write_b16 v109, v141 offset:6928
	v_fmac_f32_e32 v190, v88, v189
	v_fmac_f32_e32 v222, v88, v221
	v_fmac_f32_e32 v190, v52, v221
	v_fmac_f32_e32 v222, v139, v189
	v_cvt_pk_bf16_f32 v140, v190, v222
	ds_write_b16_d16_hi v109, v140 offset:7072
	ds_write_b16 v109, v140 offset:7200
	v_fmac_f32_e32 v191, v88, v190
	v_fmac_f32_e32 v223, v88, v222
	v_fmac_f32_e32 v191, v52, v222
	v_fmac_f32_e32 v223, v139, v190
	v_cvt_pk_bf16_f32 v141, v191, v223
	ds_write_b16_d16_hi v109, v141 offset:7344
	ds_write_b16 v109, v141 offset:7472
	s_waitcnt lgkmcnt(4)
	v_fmac_f32_e32 v204, v88, v191
	v_fmac_f32_e32 v156, v88, v223
	v_fmac_f32_e32 v204, v52, v223
	v_fmac_f32_e32 v156, v139, v191
	v_cvt_pk_bf16_f32 v140, v204, v156
	ds_write_b16_d16_hi v109, v140 offset:7616
	ds_write_b16 v109, v140 offset:7744
	v_fmac_f32_e32 v205, v88, v204
	v_fmac_f32_e32 v157, v88, v156
	v_fmac_f32_e32 v205, v52, v156
	v_fmac_f32_e32 v157, v139, v204
	v_cvt_pk_bf16_f32 v141, v205, v157
	ds_write_b16_d16_hi v109, v141 offset:7888
	ds_write_b16 v109, v141 offset:8016
	v_fmac_f32_e32 v206, v88, v205
	v_fmac_f32_e32 v158, v88, v157
	v_fmac_f32_e32 v206, v52, v157
	v_fmac_f32_e32 v158, v139, v205
	v_cvt_pk_bf16_f32 v140, v206, v158
	ds_write_b16_d16_hi v109, v140 offset:8160
	ds_write_b16 v109, v140 offset:8288
	v_fmac_f32_e32 v207, v88, v206
	v_fmac_f32_e32 v159, v88, v158
	v_fmac_f32_e32 v207, v52, v158
	v_fmac_f32_e32 v159, v139, v206
	v_cvt_pk_bf16_f32 v141, v207, v159
	ds_write_b16_d16_hi v109, v141 offset:8432
	ds_write_b16 v109, v141 offset:8560
	s_waitcnt lgkmcnt(4)
	v_mov_b32_e32 v66, v207
	v_mov_b32_e32 v67, v159
	s_waitcnt vmcnt(11)
	v_bfe_u32 v49, v7, 16, 1
	v_bfe_u32 v129, v6, 16, 1
	v_bfe_u32 v130, v5, 16, 1
	v_bfe_u32 v131, v4, 16, 1
	s_waitcnt vmcnt(5)
	v_pk_add_f32 v[8:9], v[8:9], 0 neg_lo:[1,1] neg_hi:[1,1]
	v_pk_add_f32 v[10:11], v[10:11], 0 neg_lo:[1,1] neg_hi:[1,1]
	v_add3_u32 v131, v4, v131, s43
	v_add3_u32 v130, v5, v130, s43
	v_add3_u32 v129, v6, v129, s43
	v_add3_u32 v49, v7, v49, s43
	v_bfe_u32 v4, v18, 16, 1
	v_bfe_u32 v5, v39, 16, 1
	v_bfe_u32 v6, v17, 16, 1
	v_bfe_u32 v7, v16, 16, 1
	s_waitcnt vmcnt(2)
	v_pk_add_f32 v[12:13], v[12:13], 0 neg_lo:[1,1] neg_hi:[1,1]
	v_pk_add_f32 v[14:15], v[14:15], 0 neg_lo:[1,1] neg_hi:[1,1]
	v_add3_u32 v16, v16, v7, s43
	v_add3_u32 v17, v17, v6, s43
	v_add3_u32 v39, v39, v5, s43
	v_add3_u32 v18, v18, v4, s43
	v_bfe_u32 v4, v11, 16, 1
	v_bfe_u32 v5, v10, 16, 1
	v_bfe_u32 v6, v9, 16, 1
	v_bfe_u32 v7, v8, 16, 1
	v_add3_u32 v135, v8, v7, s43
	v_add3_u32 v136, v9, v6, s43
	v_add3_u32 v137, v10, v5, s43
	v_add3_u32 v138, v11, v4, s43
	v_bfe_u32 v4, v15, 16, 1
	v_bfe_u32 v5, v14, 16, 1
	v_bfe_u32 v6, v13, 16, 1
	v_bfe_u32 v7, v12, 16, 1
	v_add3_u32 v139, v12, v7, s43
	v_add3_u32 v140, v13, v6, s43
	v_add3_u32 v141, v14, v5, s43
	v_add3_u32 v142, v15, v4, s43
	s_waitcnt lgkmcnt(0)
	ds_read_b128 v[4:7], v128
	ds_read_b128 v[12:15], v128 offset:64
	v_bfe_u32 v41, v22, 16, 1
	v_bfe_u32 v43, v19, 16, 1
	v_pk_add_f32 v[26:27], v[26:27], 0 neg_lo:[1,1] neg_hi:[1,1]
	v_bfe_u32 v45, v21, 16, 1
	v_bfe_u32 v47, v20, 16, 1
	v_add3_u32 v19, v19, v43, s43
	v_add3_u32 v41, v22, v41, s43
	v_bfe_u32 v22, v1, 16, 1
	v_bfe_u32 v43, v0, 16, 1
	v_pk_add_f32 v[24:25], v[24:25], 0 neg_lo:[1,1] neg_hi:[1,1]
	s_waitcnt vmcnt(1)
	v_pk_add_f32 v[30:31], v[30:31], 0 neg_lo:[1,1] neg_hi:[1,1]
	v_add3_u32 v47, v20, v47, s43
	v_add3_u32 v45, v21, v45, s43
	v_bfe_u32 v20, v3, 16, 1
	v_bfe_u32 v21, v2, 16, 1
	v_add3_u32 v43, v0, v43, s43
	v_add3_u32 v132, v1, v22, s43
	v_bfe_u32 v0, v27, 16, 1
	v_bfe_u32 v1, v26, 16, 1
	v_pk_add_f32 v[28:29], v[28:29], 0 neg_lo:[1,1] neg_hi:[1,1]
	v_lshl_add_u64 v[90:91], v[90:91], 1, s[6:7]
	v_add3_u32 v133, v2, v21, s43
	v_add3_u32 v134, v3, v20, s43
	v_bfe_u32 v2, v25, 16, 1
	v_bfe_u32 v3, v24, 16, 1
	v_add3_u32 v26, v26, v1, s43
	v_add3_u32 v27, v27, v0, s43
	v_bfe_u32 v0, v31, 16, 1
	v_bfe_u32 v1, v30, 16, 1
	v_lshlrev_b32_e32 v22, 15, v51
	v_mov_b32_e32 v51, v169
	v_add3_u32 v24, v24, v3, s43
	v_add3_u32 v25, v25, v2, s43
	v_bfe_u32 v2, v29, 16, 1
	v_bfe_u32 v3, v28, 16, 1
	v_add3_u32 v30, v30, v1, s43
	v_add3_u32 v31, v31, v0, s43
	v_lshl_add_u64 v[0:1], v[90:91], 0, v[50:51]
	s_mov_b64 s[4:5], 0x2d581800
	s_mov_b32 s2, 0x7060302
	v_add3_u32 v28, v28, v3, s43
	v_add3_u32 v29, v29, v2, s43
	v_lshl_add_u64 v[20:21], v[0:1], 0, s[4:5]
	v_perm_b32 v3, v19, v41, s2
	v_perm_b32 v2, v45, v47, s2
	v_perm_b32 v1, v49, v129, s2
	v_perm_b32 v0, v130, v131, s2
	s_movk_i32 s4, 0xf800
	s_waitcnt lgkmcnt(1)
	v_mfma_f32_16x16x32_bf16 v[8:11], v[4:7], v[0:3], 0
	v_perm_b32 v7, v39, v18, s2
	v_perm_b32 v6, v17, v16, s2
	ds_read_b128 v[16:19], v128 offset:128
	v_perm_b32 v5, v134, v133, s2
	v_perm_b32 v4, v132, v43, s2
	s_waitcnt lgkmcnt(1)
	s_nop 0
	v_mfma_f32_16x16x32_bf16 v[12:15], v[12:15], v[4:7], v[8:11]
	s_nop 2
	v_perm_b32 v11, v27, v26, s2
	v_perm_b32 v10, v25, v24, s2
	ds_read_b128 v[24:27], v128 offset:192
	v_perm_b32 v9, v138, v137, s2
	v_perm_b32 v8, v136, v135, s2
	s_waitcnt lgkmcnt(1)
	s_nop 0
	v_mfma_f32_16x16x32_bf16 v[16:19], v[16:19], v[8:11], v[12:15]
	s_nop 2
	v_perm_b32 v15, v31, v30, s2
	v_perm_b32 v14, v29, v28, s2
	v_perm_b32 v13, v142, v141, s2
	v_perm_b32 v12, v140, v139, s2
	s_waitcnt lgkmcnt(0)
	s_nop 0
	v_mfma_f32_16x16x32_bf16 v[16:19], v[24:27], v[12:15], v[16:19]
	ds_read_b32 v24, v112
	s_waitcnt vmcnt(0) lgkmcnt(0)
	s_nop 5
	v_fma_f32 v16, v23, v24, v16
	v_mul_f32_e32 v24, 0x3d372713, v16
	v_mul_f32_e32 v24, v16, v24
	v_fma_f32 v24, v16, v24, v16
	v_mul_f32_e32 v24, 0x3f4c422a, v24
	v_add_f32_e32 v24, v24, v24
	v_mul_f32_e32 v24, 0x3fb8aa3b, v24
	v_exp_f32_e32 v24, v24
	v_mul_f32_e32 v16, 0.5, v16
	v_add_f32_e32 v24, 1.0, v24
	v_rcp_f32_e32 v24, v24
	s_nop 0
	v_fma_f32 v24, v24, -2.0, 1.0
	v_add_f32_e32 v24, 1.0, v24
	v_mul_f32_e32 v16, v16, v24
	v_bfe_u32 v24, v16, 16, 1
	v_add3_u32 v16, v16, v24, s43
	v_or_b32_e32 v24, v22, v93
	v_lshlrev_b32_e32 v168, 1, v24
	v_lshl_add_u64 v[24:25], v[20:21], 0, v[168:169]
	global_store_short_d16_hi v[24:25], v16, off
	ds_read_b32 v16, v113
	s_waitcnt lgkmcnt(0)
	v_fma_f32 v16, v23, v16, v17
	v_mul_f32_e32 v17, 0x3d372713, v16
	v_mul_f32_e32 v17, v16, v17
	v_fma_f32 v17, v16, v17, v16
	v_mul_f32_e32 v17, 0x3f4c422a, v17
	v_add_f32_e32 v17, v17, v17
	v_mul_f32_e32 v17, 0x3fb8aa3b, v17
	v_exp_f32_e32 v17, v17
	v_mul_f32_e32 v16, 0.5, v16
	v_add_f32_e32 v17, 1.0, v17
	v_rcp_f32_e32 v17, v17
	s_nop 0
	v_fma_f32 v17, v17, -2.0, 1.0
	v_add_f32_e32 v17, 1.0, v17
	v_mul_f32_e32 v16, v16, v17
	v_bfe_u32 v17, v16, 16, 1
	v_add3_u32 v24, v16, v17, s43
	v_or_b32_e32 v16, v22, v94
	v_lshlrev_b32_e32 v168, 1, v16
	v_lshl_add_u64 v[16:17], v[20:21], 0, v[168:169]
	global_store_short_d16_hi v[16:17], v24, off
	ds_read_b32 v16, v114
	ds_read_b128 v[24:27], v128 offset:4416
	s_waitcnt lgkmcnt(1)
	v_fma_f32 v16, v23, v16, v18
	v_mul_f32_e32 v17, 0x3d372713, v16
	v_mul_f32_e32 v17, v16, v17
	v_fma_f32 v17, v16, v17, v16
	v_mul_f32_e32 v17, 0x3f4c422a, v17
	v_add_f32_e32 v17, v17, v17
	v_mul_f32_e32 v17, 0x3fb8aa3b, v17
	v_exp_f32_e32 v17, v17
	v_mul_f32_e32 v16, 0.5, v16
	v_add_f32_e32 v17, 1.0, v17
	v_rcp_f32_e32 v17, v17
	s_nop 0
	v_fma_f32 v17, v17, -2.0, 1.0
	v_add_f32_e32 v17, 1.0, v17
	v_mul_f32_e32 v16, v16, v17
	v_bfe_u32 v17, v16, 16, 1
	v_add3_u32 v18, v16, v17, s43
	v_or_b32_e32 v16, v22, v95
	v_lshlrev_b32_e32 v168, 1, v16
	v_lshl_add_u64 v[16:17], v[20:21], 0, v[168:169]
	global_store_short_d16_hi v[16:17], v18, off
	ds_read_b32 v16, v115
	s_waitcnt lgkmcnt(0)
	v_fmac_f32_e32 v19, v23, v16
	v_mul_f32_e32 v16, 0x3d372713, v19
	v_mul_f32_e32 v16, v19, v16
	v_fma_f32 v16, v19, v16, v19
	v_mul_f32_e32 v16, 0x3f4c422a, v16
	v_add_f32_e32 v16, v16, v16
	v_mul_f32_e32 v16, 0x3fb8aa3b, v16
	v_exp_f32_e32 v16, v16
	v_mul_f32_e32 v17, 0.5, v19
	v_add_f32_e32 v16, 1.0, v16
	v_rcp_f32_e32 v16, v16
	s_nop 0
	v_fma_f32 v16, v16, -2.0, 1.0
	v_add_f32_e32 v16, 1.0, v16
	v_mul_f32_e32 v16, v17, v16
	v_bfe_u32 v17, v16, 16, 1
	v_add3_u32 v18, v16, v17, s43
	v_or_b32_e32 v16, v22, v96
	v_lshlrev_b32_e32 v168, 1, v16
	v_lshl_add_u64 v[16:17], v[20:21], 0, v[168:169]
	global_store_short_d16_hi v[16:17], v18, off
	ds_read_b128 v[16:19], v128 offset:4352
	s_waitcnt lgkmcnt(0)
	v_mfma_f32_16x16x32_bf16 v[16:19], v[16:19], v[0:3], 0
	v_mfma_f32_16x16x32_bf16 v[16:19], v[24:27], v[4:7], v[16:19]
	ds_read_b128 v[24:27], v128 offset:4480
	s_waitcnt lgkmcnt(0)
	v_mfma_f32_16x16x32_bf16 v[16:19], v[24:27], v[8:11], v[16:19]
	ds_read_b128 v[24:27], v128 offset:4544
	s_waitcnt lgkmcnt(0)
	v_mfma_f32_16x16x32_bf16 v[16:19], v[24:27], v[12:15], v[16:19]
	ds_read_b32 v24, v116
	s_waitcnt lgkmcnt(0)
	s_nop 5
	v_fma_f32 v16, v23, v24, v16
	v_mul_f32_e32 v24, 0x3d372713, v16
	v_mul_f32_e32 v24, v16, v24
	v_fma_f32 v24, v16, v24, v16
	v_mul_f32_e32 v24, 0x3f4c422a, v24
	v_add_f32_e32 v24, v24, v24
	v_mul_f32_e32 v24, 0x3fb8aa3b, v24
	v_exp_f32_e32 v24, v24
	v_mul_f32_e32 v16, 0.5, v16
	v_add_f32_e32 v24, 1.0, v24
	v_rcp_f32_e32 v24, v24
	s_nop 0
	v_fma_f32 v24, v24, -2.0, 1.0
	v_add_f32_e32 v24, 1.0, v24
	v_mul_f32_e32 v16, v16, v24
	v_bfe_u32 v24, v16, 16, 1
	v_add3_u32 v16, v16, v24, s43
	v_or_b32_e32 v24, v22, v97
	v_lshlrev_b32_e32 v168, 1, v24
	v_lshl_add_u64 v[24:25], v[20:21], 0, v[168:169]
	global_store_short_d16_hi v[24:25], v16, off
	ds_read_b32 v16, v117
	s_waitcnt lgkmcnt(0)
	v_fma_f32 v16, v23, v16, v17
	v_mul_f32_e32 v17, 0x3d372713, v16
	v_mul_f32_e32 v17, v16, v17
	v_fma_f32 v17, v16, v17, v16
	v_mul_f32_e32 v17, 0x3f4c422a, v17
	v_add_f32_e32 v17, v17, v17
	v_mul_f32_e32 v17, 0x3fb8aa3b, v17
	v_exp_f32_e32 v17, v17
	v_mul_f32_e32 v16, 0.5, v16
	v_add_f32_e32 v17, 1.0, v17
	v_rcp_f32_e32 v17, v17
	s_nop 0
	v_fma_f32 v17, v17, -2.0, 1.0
	v_add_f32_e32 v17, 1.0, v17
	v_mul_f32_e32 v16, v16, v17
	v_bfe_u32 v17, v16, 16, 1
	v_add3_u32 v24, v16, v17, s43
	v_or_b32_e32 v16, v22, v98
	v_lshlrev_b32_e32 v168, 1, v16
	v_lshl_add_u64 v[16:17], v[20:21], 0, v[168:169]
	global_store_short_d16_hi v[16:17], v24, off
	ds_read_b32 v16, v118
	s_waitcnt lgkmcnt(0)
	v_fma_f32 v16, v23, v16, v18
	v_mul_f32_e32 v17, 0x3d372713, v16
	v_mul_f32_e32 v17, v16, v17
	v_fma_f32 v17, v16, v17, v16
	v_mul_f32_e32 v17, 0x3f4c422a, v17
	v_add_f32_e32 v17, v17, v17
	v_mul_f32_e32 v17, 0x3fb8aa3b, v17
	v_exp_f32_e32 v17, v17
	v_mul_f32_e32 v16, 0.5, v16
	v_add_f32_e32 v17, 1.0, v17
	v_rcp_f32_e32 v17, v17
	s_nop 0
	v_fma_f32 v17, v17, -2.0, 1.0
	v_add_f32_e32 v17, 1.0, v17
	v_mul_f32_e32 v16, v16, v17
	v_bfe_u32 v17, v16, 16, 1
	v_add3_u32 v18, v16, v17, s43
	v_or_b32_e32 v16, v22, v99
	v_lshlrev_b32_e32 v168, 1, v16
	v_lshl_add_u64 v[16:17], v[20:21], 0, v[168:169]
	global_store_short_d16_hi v[16:17], v18, off
	ds_read_b32 v16, v119
	s_waitcnt lgkmcnt(0)
	v_fmac_f32_e32 v19, v23, v16
	v_mul_f32_e32 v16, 0x3d372713, v19
	v_mul_f32_e32 v16, v19, v16
	v_fma_f32 v16, v19, v16, v19
	v_mul_f32_e32 v16, 0x3f4c422a, v16
	v_add_f32_e32 v16, v16, v16
	v_mul_f32_e32 v16, 0x3fb8aa3b, v16
	v_exp_f32_e32 v16, v16
	v_mul_f32_e32 v17, 0.5, v19
	v_add_f32_e32 v16, 1.0, v16
	v_rcp_f32_e32 v16, v16
	s_nop 0
	v_fma_f32 v16, v16, -2.0, 1.0
	v_add_f32_e32 v16, 1.0, v16
	v_mul_f32_e32 v16, v17, v16
	v_bfe_u32 v17, v16, 16, 1
	v_add3_u32 v18, v16, v17, s43
	v_or_b32_e32 v16, v22, v100
	v_lshlrev_b32_e32 v168, 1, v16
	v_lshl_add_u64 v[16:17], v[20:21], 0, v[168:169]
	global_store_short_d16_hi v[16:17], v18, off
	s_waitcnt lgkmcnt(0)
	v_mov_b32_e32 v16, v109
.LBB0_882:
	ds_read_b128 v[130:133], v252 offset:2048
	ds_read_b128 v[134:137], v252 offset:2064
	v_sub_f32_e32 v139, 0, v52
	s_waitcnt lgkmcnt(0)
	s_nop 1
	v_mfma_f32_32x32x2_f32 v[176:191], v130, v54, 0
	v_mfma_f32_32x32x2_f32 v[192:207], v130, v72, 0
	v_mfma_f32_32x32x2_f32 v[208:223], v130, v55, 0
	v_mfma_f32_32x32x2_f32 v[144:159], v130, v73, 0
	v_mfma_f32_32x32x2_f32 v[176:191], v131, v56, v[176:191]
	v_mfma_f32_32x32x2_f32 v[192:207], v131, v74, v[192:207]
	v_mfma_f32_32x32x2_f32 v[208:223], v131, v57, v[208:223]
	v_mfma_f32_32x32x2_f32 v[144:159], v131, v75, v[144:159]
	v_mfma_f32_32x32x2_f32 v[176:191], v132, v58, v[176:191]
	v_mfma_f32_32x32x2_f32 v[192:207], v132, v76, v[192:207]
	v_mfma_f32_32x32x2_f32 v[208:223], v132, v59, v[208:223]
	v_mfma_f32_32x32x2_f32 v[144:159], v132, v77, v[144:159]
	v_mfma_f32_32x32x2_f32 v[176:191], v133, v60, v[176:191]
	v_mfma_f32_32x32x2_f32 v[192:207], v133, v78, v[192:207]
	v_mfma_f32_32x32x2_f32 v[208:223], v133, v61, v[208:223]
	v_mfma_f32_32x32x2_f32 v[144:159], v133, v79, v[144:159]
	v_mfma_f32_32x32x2_f32 v[176:191], v134, v62, v[176:191]
	v_mfma_f32_32x32x2_f32 v[192:207], v134, v80, v[192:207]
	v_mfma_f32_32x32x2_f32 v[208:223], v134, v63, v[208:223]
	v_mfma_f32_32x32x2_f32 v[144:159], v134, v81, v[144:159]
	v_mfma_f32_32x32x2_f32 v[176:191], v135, v64, v[176:191]
	v_mfma_f32_32x32x2_f32 v[192:207], v135, v82, v[192:207]
	v_mfma_f32_32x32x2_f32 v[208:223], v135, v65, v[208:223]
	v_mfma_f32_32x32x2_f32 v[144:159], v135, v83, v[144:159]
	v_mfma_f32_32x32x2_f32 v[176:191], v136, v68, v[176:191]
	v_mfma_f32_32x32x2_f32 v[192:207], v136, v84, v[192:207]
	v_mfma_f32_32x32x2_f32 v[208:223], v136, v69, v[208:223]
	v_mfma_f32_32x32x2_f32 v[144:159], v136, v85, v[144:159]
	v_mfma_f32_32x32x2_f32 v[176:191], v137, v70, v[176:191]
	v_mfma_f32_32x32x2_f32 v[192:207], v137, v86, v[192:207]
	v_mfma_f32_32x32x2_f32 v[208:223], v137, v71, v[208:223]
	v_mfma_f32_32x32x2_f32 v[144:159], v137, v87, v[144:159]
	s_nop 7
	s_nop 7
	s_nop 3
	v_permlane32_swap_b32_e32 v176, v192
	v_permlane32_swap_b32_e32 v208, v144
	v_permlane32_swap_b32_e32 v177, v193
	v_permlane32_swap_b32_e32 v209, v145
	v_permlane32_swap_b32_e32 v178, v194
	v_permlane32_swap_b32_e32 v210, v146
	v_permlane32_swap_b32_e32 v179, v195
	v_permlane32_swap_b32_e32 v211, v147
	v_permlane32_swap_b32_e32 v180, v196
	v_permlane32_swap_b32_e32 v212, v148
	v_permlane32_swap_b32_e32 v181, v197
	v_permlane32_swap_b32_e32 v213, v149
	v_permlane32_swap_b32_e32 v182, v198
	v_permlane32_swap_b32_e32 v214, v150
	v_permlane32_swap_b32_e32 v183, v199
	v_permlane32_swap_b32_e32 v215, v151
	v_permlane32_swap_b32_e32 v184, v200
	v_permlane32_swap_b32_e32 v216, v152
	v_permlane32_swap_b32_e32 v185, v201
	v_permlane32_swap_b32_e32 v217, v153
	v_permlane32_swap_b32_e32 v186, v202
	v_permlane32_swap_b32_e32 v218, v154
	v_permlane32_swap_b32_e32 v187, v203
	v_permlane32_swap_b32_e32 v219, v155
	v_permlane32_swap_b32_e32 v188, v204
	v_permlane32_swap_b32_e32 v220, v156
	v_permlane32_swap_b32_e32 v189, v205
	v_permlane32_swap_b32_e32 v221, v157
	v_permlane32_swap_b32_e32 v190, v206
	v_permlane32_swap_b32_e32 v222, v158
	v_permlane32_swap_b32_e32 v191, v207
	v_permlane32_swap_b32_e32 v223, v159
	s_nop 1
	v_fmac_f32_e32 v176, v88, v66
	v_fmac_f32_e32 v208, v88, v67
	v_fmac_f32_e32 v176, v52, v67
	v_fmac_f32_e32 v208, v139, v66
	v_cvt_pk_bf16_f32 v140, v176, v208
	ds_write_b16_d16_hi v109, v140
	ds_write_b16 v109, v140 offset:128
	v_fmac_f32_e32 v177, v88, v176
	v_fmac_f32_e32 v209, v88, v208
	v_fmac_f32_e32 v177, v52, v208
	v_fmac_f32_e32 v209, v139, v176
	v_cvt_pk_bf16_f32 v141, v177, v209
	ds_write_b16_d16_hi v109, v141 offset:272
	ds_write_b16 v109, v141 offset:400
	v_fmac_f32_e32 v178, v88, v177
	v_fmac_f32_e32 v210, v88, v209
	v_fmac_f32_e32 v178, v52, v209
	v_fmac_f32_e32 v210, v139, v177
	v_cvt_pk_bf16_f32 v140, v178, v210
	ds_write_b16_d16_hi v109, v140 offset:544
	ds_write_b16 v109, v140 offset:672
	v_fmac_f32_e32 v179, v88, v178
	v_fmac_f32_e32 v211, v88, v210
	v_fmac_f32_e32 v179, v52, v210
	v_fmac_f32_e32 v211, v139, v178
	v_cvt_pk_bf16_f32 v141, v179, v211
	ds_write_b16_d16_hi v109, v141 offset:816
	ds_write_b16 v109, v141 offset:944
	s_waitcnt lgkmcnt(4)
	v_fmac_f32_e32 v192, v88, v179
	v_fmac_f32_e32 v144, v88, v211
	v_fmac_f32_e32 v192, v52, v211
	v_fmac_f32_e32 v144, v139, v179
	v_cvt_pk_bf16_f32 v140, v192, v144
	ds_write_b16_d16_hi v109, v140 offset:1088
	ds_write_b16 v109, v140 offset:1216
	v_fmac_f32_e32 v193, v88, v192
	v_fmac_f32_e32 v145, v88, v144
	v_fmac_f32_e32 v193, v52, v144
	v_fmac_f32_e32 v145, v139, v192
	v_cvt_pk_bf16_f32 v141, v193, v145
	ds_write_b16_d16_hi v109, v141 offset:1360
	ds_write_b16 v109, v141 offset:1488
	v_fmac_f32_e32 v194, v88, v193
	v_fmac_f32_e32 v146, v88, v145
	v_fmac_f32_e32 v194, v52, v145
	v_fmac_f32_e32 v146, v139, v193
	v_cvt_pk_bf16_f32 v140, v194, v146
	ds_write_b16_d16_hi v109, v140 offset:1632
	ds_write_b16 v109, v140 offset:1760
	v_fmac_f32_e32 v195, v88, v194
	v_fmac_f32_e32 v147, v88, v146
	v_fmac_f32_e32 v195, v52, v146
	v_fmac_f32_e32 v147, v139, v194
	v_cvt_pk_bf16_f32 v141, v195, v147
	ds_write_b16_d16_hi v109, v141 offset:1904
	ds_write_b16 v109, v141 offset:2032
	s_waitcnt lgkmcnt(4)
	v_fmac_f32_e32 v180, v88, v195
	v_fmac_f32_e32 v212, v88, v147
	v_fmac_f32_e32 v180, v52, v147
	v_fmac_f32_e32 v212, v139, v195
	v_cvt_pk_bf16_f32 v140, v180, v212
	ds_write_b16_d16_hi v109, v140 offset:2176
	ds_write_b16 v109, v140 offset:2304
	v_fmac_f32_e32 v181, v88, v180
	v_fmac_f32_e32 v213, v88, v212
	v_fmac_f32_e32 v181, v52, v212
	v_fmac_f32_e32 v213, v139, v180
	v_cvt_pk_bf16_f32 v141, v181, v213
	ds_write_b16_d16_hi v109, v141 offset:2448
	ds_write_b16 v109, v141 offset:2576
	v_fmac_f32_e32 v182, v88, v181
	v_fmac_f32_e32 v214, v88, v213
	v_fmac_f32_e32 v182, v52, v213
	v_fmac_f32_e32 v214, v139, v181
	v_cvt_pk_bf16_f32 v140, v182, v214
	ds_write_b16_d16_hi v109, v140 offset:2720
	ds_write_b16 v109, v140 offset:2848
	v_fmac_f32_e32 v183, v88, v182
	v_fmac_f32_e32 v215, v88, v214
	v_fmac_f32_e32 v183, v52, v214
	v_fmac_f32_e32 v215, v139, v182
	v_cvt_pk_bf16_f32 v141, v183, v215
	ds_write_b16_d16_hi v109, v141 offset:2992
	ds_write_b16 v109, v141 offset:3120
	s_waitcnt lgkmcnt(4)
	v_fmac_f32_e32 v196, v88, v183
	v_fmac_f32_e32 v148, v88, v215
	v_fmac_f32_e32 v196, v52, v215
	v_fmac_f32_e32 v148, v139, v183
	v_cvt_pk_bf16_f32 v140, v196, v148
	ds_write_b16_d16_hi v109, v140 offset:3264
	ds_write_b16 v109, v140 offset:3392
	v_fmac_f32_e32 v197, v88, v196
	v_fmac_f32_e32 v149, v88, v148
	v_fmac_f32_e32 v197, v52, v148
	v_fmac_f32_e32 v149, v139, v196
	v_cvt_pk_bf16_f32 v141, v197, v149
	ds_write_b16_d16_hi v109, v141 offset:3536
	ds_write_b16 v109, v141 offset:3664
	v_fmac_f32_e32 v198, v88, v197
	v_fmac_f32_e32 v150, v88, v149
	v_fmac_f32_e32 v198, v52, v149
	v_fmac_f32_e32 v150, v139, v197
	v_cvt_pk_bf16_f32 v140, v198, v150
	ds_write_b16_d16_hi v109, v140 offset:3808
	ds_write_b16 v109, v140 offset:3936
	v_fmac_f32_e32 v199, v88, v198
	v_fmac_f32_e32 v151, v88, v150
	v_fmac_f32_e32 v199, v52, v150
	v_fmac_f32_e32 v151, v139, v198
	v_cvt_pk_bf16_f32 v141, v199, v151
	ds_write_b16_d16_hi v109, v141 offset:4080
	ds_write_b16 v109, v141 offset:4208
	s_waitcnt lgkmcnt(4)
	v_fmac_f32_e32 v184, v88, v199
	v_fmac_f32_e32 v216, v88, v151
	v_fmac_f32_e32 v184, v52, v151
	v_fmac_f32_e32 v216, v139, v199
	v_cvt_pk_bf16_f32 v140, v184, v216
	ds_write_b16_d16_hi v109, v140 offset:4352
	ds_write_b16 v109, v140 offset:4480
	v_fmac_f32_e32 v185, v88, v184
	v_fmac_f32_e32 v217, v88, v216
	v_fmac_f32_e32 v185, v52, v216
	v_fmac_f32_e32 v217, v139, v184
	v_cvt_pk_bf16_f32 v141, v185, v217
	ds_write_b16_d16_hi v109, v141 offset:4624
	ds_write_b16 v109, v141 offset:4752
	v_fmac_f32_e32 v186, v88, v185
	v_fmac_f32_e32 v218, v88, v217
	v_fmac_f32_e32 v186, v52, v217
	v_fmac_f32_e32 v218, v139, v185
	v_cvt_pk_bf16_f32 v140, v186, v218
	ds_write_b16_d16_hi v109, v140 offset:4896
	ds_write_b16 v109, v140 offset:5024
	v_fmac_f32_e32 v187, v88, v186
	v_fmac_f32_e32 v219, v88, v218
	v_fmac_f32_e32 v187, v52, v218
	v_fmac_f32_e32 v219, v139, v186
	v_cvt_pk_bf16_f32 v141, v187, v219
	ds_write_b16_d16_hi v109, v141 offset:5168
	ds_write_b16 v109, v141 offset:5296
	s_waitcnt lgkmcnt(4)
	v_fmac_f32_e32 v200, v88, v187
	v_fmac_f32_e32 v152, v88, v219
	v_fmac_f32_e32 v200, v52, v219
	v_fmac_f32_e32 v152, v139, v187
	v_cvt_pk_bf16_f32 v140, v200, v152
	ds_write_b16_d16_hi v109, v140 offset:5440
	ds_write_b16 v109, v140 offset:5568
	v_fmac_f32_e32 v201, v88, v200
	v_fmac_f32_e32 v153, v88, v152
	v_fmac_f32_e32 v201, v52, v152
	v_fmac_f32_e32 v153, v139, v200
	v_cvt_pk_bf16_f32 v141, v201, v153
	ds_write_b16_d16_hi v109, v141 offset:5712
	ds_write_b16 v109, v141 offset:5840
	v_fmac_f32_e32 v202, v88, v201
	v_fmac_f32_e32 v154, v88, v153
	v_fmac_f32_e32 v202, v52, v153
	v_fmac_f32_e32 v154, v139, v201
	v_cvt_pk_bf16_f32 v140, v202, v154
	ds_write_b16_d16_hi v109, v140 offset:5984
	ds_write_b16 v109, v140 offset:6112
	v_fmac_f32_e32 v203, v88, v202
	v_fmac_f32_e32 v155, v88, v154
	v_fmac_f32_e32 v203, v52, v154
	v_fmac_f32_e32 v155, v139, v202
	v_cvt_pk_bf16_f32 v141, v203, v155
	ds_write_b16_d16_hi v109, v141 offset:6256
	ds_write_b16 v109, v141 offset:6384
	s_waitcnt lgkmcnt(4)
	v_fmac_f32_e32 v188, v88, v203
	v_fmac_f32_e32 v220, v88, v155
	v_fmac_f32_e32 v188, v52, v155
	v_fmac_f32_e32 v220, v139, v203
	v_cvt_pk_bf16_f32 v140, v188, v220
	ds_write_b16_d16_hi v109, v140 offset:6528
	ds_write_b16 v109, v140 offset:6656
	v_fmac_f32_e32 v189, v88, v188
	v_fmac_f32_e32 v221, v88, v220
	v_fmac_f32_e32 v189, v52, v220
	v_fmac_f32_e32 v221, v139, v188
	v_cvt_pk_bf16_f32 v141, v189, v221
	ds_write_b16_d16_hi v109, v141 offset:6800
	ds_write_b16 v109, v141 offset:6928
	v_fmac_f32_e32 v190, v88, v189
	v_fmac_f32_e32 v222, v88, v221
	v_fmac_f32_e32 v190, v52, v221
	v_fmac_f32_e32 v222, v139, v189
	v_cvt_pk_bf16_f32 v140, v190, v222
	ds_write_b16_d16_hi v109, v140 offset:7072
	ds_write_b16 v109, v140 offset:7200
	v_fmac_f32_e32 v191, v88, v190
	v_fmac_f32_e32 v223, v88, v222
	v_fmac_f32_e32 v191, v52, v222
	v_fmac_f32_e32 v223, v139, v190
	v_cvt_pk_bf16_f32 v141, v191, v223
	ds_write_b16_d16_hi v109, v141 offset:7344
	ds_write_b16 v109, v141 offset:7472
	s_waitcnt lgkmcnt(4)
	v_fmac_f32_e32 v204, v88, v191
	v_fmac_f32_e32 v156, v88, v223
	v_fmac_f32_e32 v204, v52, v223
	v_fmac_f32_e32 v156, v139, v191
	v_cvt_pk_bf16_f32 v140, v204, v156
	ds_write_b16_d16_hi v109, v140 offset:7616
	ds_write_b16 v109, v140 offset:7744
	v_fmac_f32_e32 v205, v88, v204
	v_fmac_f32_e32 v157, v88, v156
	v_fmac_f32_e32 v205, v52, v156
	v_fmac_f32_e32 v157, v139, v204
	v_cvt_pk_bf16_f32 v141, v205, v157
	ds_write_b16_d16_hi v109, v141 offset:7888
	ds_write_b16 v109, v141 offset:8016
	v_fmac_f32_e32 v206, v88, v205
	v_fmac_f32_e32 v158, v88, v157
	v_fmac_f32_e32 v206, v52, v157
	v_fmac_f32_e32 v158, v139, v205
	v_cvt_pk_bf16_f32 v140, v206, v158
	ds_write_b16_d16_hi v109, v140 offset:8160
	ds_write_b16 v109, v140 offset:8288
	v_fmac_f32_e32 v207, v88, v206
	v_fmac_f32_e32 v159, v88, v158
	v_fmac_f32_e32 v207, v52, v158
	v_fmac_f32_e32 v159, v139, v206
	v_cvt_pk_bf16_f32 v141, v207, v159
	ds_write_b16_d16_hi v109, v141 offset:8432
	ds_write_b16 v109, v141 offset:8560
	s_waitcnt lgkmcnt(4)
	v_mov_b32_e32 v66, v207
	v_mov_b32_e32 v67, v159
	s_waitcnt lgkmcnt(0)
	ds_read_b128 v[16:19], v128
	ds_read_b128 v[24:27], v128 offset:64
	v_add_u32_e32 v33, s19, v33
	s_movk_i32 s2, 0xfff
	v_cmp_lt_i32_e32 vcc, s2, v33
	s_or_b64 s[22:23], vcc, s[22:23]
	s_waitcnt lgkmcnt(1)
	v_mfma_f32_16x16x32_bf16 v[16:19], v[16:19], v[0:3], 0
	s_waitcnt lgkmcnt(0)
	v_mfma_f32_16x16x32_bf16 v[16:19], v[24:27], v[4:7], v[16:19]
	ds_read_b128 v[24:27], v128 offset:128
	s_waitcnt lgkmcnt(0)
	v_mfma_f32_16x16x32_bf16 v[16:19], v[24:27], v[8:11], v[16:19]
	ds_read_b128 v[24:27], v128 offset:192
	s_waitcnt lgkmcnt(0)
	v_mfma_f32_16x16x32_bf16 v[16:19], v[24:27], v[12:15], v[16:19]
	ds_read_b32 v24, v120
	s_waitcnt lgkmcnt(0)
	s_nop 5
	v_fma_f32 v16, v23, v24, v16
	v_mul_f32_e32 v24, 0x3d372713, v16
	v_mul_f32_e32 v24, v16, v24
	v_fma_f32 v24, v16, v24, v16
	v_mul_f32_e32 v24, 0x3f4c422a, v24
	v_add_f32_e32 v24, v24, v24
	v_mul_f32_e32 v24, 0x3fb8aa3b, v24
	v_exp_f32_e32 v24, v24
	v_mul_f32_e32 v16, 0.5, v16
	v_add_f32_e32 v24, 1.0, v24
	v_rcp_f32_e32 v24, v24
	s_nop 0
	v_fma_f32 v24, v24, -2.0, 1.0
	v_add_f32_e32 v24, 1.0, v24
	v_mul_f32_e32 v16, v16, v24
	v_bfe_u32 v24, v16, 16, 1
	v_add3_u32 v16, v16, v24, s43
	v_or_b32_e32 v24, v22, v101
	v_lshlrev_b32_e32 v168, 1, v24
	v_lshl_add_u64 v[24:25], v[20:21], 0, v[168:169]
	global_store_short_d16_hi v[24:25], v16, off
	ds_read_b32 v16, v121
	s_waitcnt lgkmcnt(0)
	v_fma_f32 v16, v23, v16, v17
	v_mul_f32_e32 v17, 0x3d372713, v16
	v_mul_f32_e32 v17, v16, v17
	v_fma_f32 v17, v16, v17, v16
	v_mul_f32_e32 v17, 0x3f4c422a, v17
	v_add_f32_e32 v17, v17, v17
	v_mul_f32_e32 v17, 0x3fb8aa3b, v17
	v_exp_f32_e32 v17, v17
	v_mul_f32_e32 v16, 0.5, v16
	v_add_f32_e32 v17, 1.0, v17
	v_rcp_f32_e32 v17, v17
	s_nop 0
	v_fma_f32 v17, v17, -2.0, 1.0
	v_add_f32_e32 v17, 1.0, v17
	v_mul_f32_e32 v16, v16, v17
	v_bfe_u32 v17, v16, 16, 1
	v_add3_u32 v24, v16, v17, s43
	v_or_b32_e32 v16, v22, v102
	v_lshlrev_b32_e32 v168, 1, v16
	v_lshl_add_u64 v[16:17], v[20:21], 0, v[168:169]
	global_store_short_d16_hi v[16:17], v24, off
	ds_read_b32 v16, v122
	s_waitcnt lgkmcnt(0)
	v_fma_f32 v16, v23, v16, v18
	v_mul_f32_e32 v17, 0x3d372713, v16
	v_mul_f32_e32 v17, v16, v17
	v_fma_f32 v17, v16, v17, v16
	v_mul_f32_e32 v17, 0x3f4c422a, v17
	v_add_f32_e32 v17, v17, v17
	v_mul_f32_e32 v17, 0x3fb8aa3b, v17
	v_exp_f32_e32 v17, v17
	v_mul_f32_e32 v16, 0.5, v16
	v_add_f32_e32 v17, 1.0, v17
	v_rcp_f32_e32 v17, v17
	s_nop 0
	v_fma_f32 v17, v17, -2.0, 1.0
	v_add_f32_e32 v17, 1.0, v17
	v_mul_f32_e32 v16, v16, v17
	v_bfe_u32 v17, v16, 16, 1
	v_add3_u32 v18, v16, v17, s43
	v_or_b32_e32 v16, v22, v103
	v_lshlrev_b32_e32 v168, 1, v16
	v_lshl_add_u64 v[16:17], v[20:21], 0, v[168:169]
	global_store_short_d16_hi v[16:17], v18, off
	ds_read_b32 v16, v123
	s_waitcnt lgkmcnt(0)
	v_fmac_f32_e32 v19, v23, v16
	v_mul_f32_e32 v16, 0x3d372713, v19
	v_mul_f32_e32 v16, v19, v16
	v_fma_f32 v16, v19, v16, v19
	v_mul_f32_e32 v16, 0x3f4c422a, v16
	v_add_f32_e32 v16, v16, v16
	v_mul_f32_e32 v16, 0x3fb8aa3b, v16
	v_exp_f32_e32 v16, v16
	v_mul_f32_e32 v17, 0.5, v19
	v_add_f32_e32 v16, 1.0, v16
	v_rcp_f32_e32 v16, v16
	s_nop 0
	v_fma_f32 v16, v16, -2.0, 1.0
	v_add_f32_e32 v16, 1.0, v16
	v_mul_f32_e32 v16, v17, v16
	v_bfe_u32 v17, v16, 16, 1
	v_add3_u32 v18, v16, v17, s43
	v_or_b32_e32 v16, v22, v104
	v_lshlrev_b32_e32 v168, 1, v16
	v_lshl_add_u64 v[16:17], v[20:21], 0, v[168:169]
	global_store_short_d16_hi v[16:17], v18, off
	ds_read_b128 v[16:19], v128 offset:4352
	s_waitcnt lgkmcnt(0)
	v_mfma_f32_16x16x32_bf16 v[0:3], v[16:19], v[0:3], 0
	ds_read_b128 v[16:19], v128 offset:4416
	s_waitcnt lgkmcnt(0)
	v_mfma_f32_16x16x32_bf16 v[0:3], v[16:19], v[4:7], v[0:3]
	ds_read_b128 v[4:7], v128 offset:4480
	s_waitcnt lgkmcnt(0)
	v_mfma_f32_16x16x32_bf16 v[0:3], v[4:7], v[8:11], v[0:3]
	ds_read_b128 v[4:7], v128 offset:4544
	s_waitcnt lgkmcnt(0)
	v_mfma_f32_16x16x32_bf16 v[0:3], v[4:7], v[12:15], v[0:3]
	ds_read_b32 v4, v124
	s_waitcnt lgkmcnt(0)
	s_nop 5
	v_fma_f32 v0, v23, v4, v0
	v_mul_f32_e32 v4, 0x3d372713, v0
	v_mul_f32_e32 v4, v0, v4
	v_fma_f32 v4, v0, v4, v0
	v_mul_f32_e32 v4, 0x3f4c422a, v4
	v_add_f32_e32 v4, v4, v4
	v_mul_f32_e32 v4, 0x3fb8aa3b, v4
	v_exp_f32_e32 v4, v4
	v_mul_f32_e32 v0, 0.5, v0
	v_add_f32_e32 v4, 1.0, v4
	v_rcp_f32_e32 v4, v4
	s_nop 0
	v_fma_f32 v4, v4, -2.0, 1.0
	v_add_f32_e32 v4, 1.0, v4
	v_mul_f32_e32 v0, v0, v4
	v_bfe_u32 v4, v0, 16, 1
	v_add3_u32 v0, v0, v4, s43
	v_or_b32_e32 v4, v22, v105
	v_lshlrev_b32_e32 v168, 1, v4
	v_lshl_add_u64 v[4:5], v[20:21], 0, v[168:169]
	global_store_short_d16_hi v[4:5], v0, off
	ds_read_b32 v0, v125
	s_waitcnt lgkmcnt(0)
	v_fma_f32 v0, v23, v0, v1
	v_mul_f32_e32 v1, 0x3d372713, v0
	v_mul_f32_e32 v1, v0, v1
	v_fma_f32 v1, v0, v1, v0
	v_mul_f32_e32 v1, 0x3f4c422a, v1
	v_add_f32_e32 v1, v1, v1
	v_mul_f32_e32 v1, 0x3fb8aa3b, v1
	v_exp_f32_e32 v1, v1
	v_mul_f32_e32 v0, 0.5, v0
	v_add_f32_e32 v1, 1.0, v1
	v_rcp_f32_e32 v1, v1
	s_nop 0
	v_fma_f32 v1, v1, -2.0, 1.0
	v_add_f32_e32 v1, 1.0, v1
	v_mul_f32_e32 v0, v0, v1
	v_bfe_u32 v1, v0, 16, 1
	v_add3_u32 v4, v0, v1, s43
	v_or_b32_e32 v0, v22, v106
	v_lshlrev_b32_e32 v168, 1, v0
	v_lshl_add_u64 v[0:1], v[20:21], 0, v[168:169]
	global_store_short_d16_hi v[0:1], v4, off
	ds_read_b32 v0, v126
	s_waitcnt lgkmcnt(0)
	v_fma_f32 v0, v23, v0, v2
	v_mul_f32_e32 v1, 0x3d372713, v0
	v_mul_f32_e32 v1, v0, v1
	v_fma_f32 v1, v0, v1, v0
	v_mul_f32_e32 v1, 0x3f4c422a, v1
	v_add_f32_e32 v1, v1, v1
	v_mul_f32_e32 v1, 0x3fb8aa3b, v1
	v_exp_f32_e32 v1, v1
	v_mul_f32_e32 v0, 0.5, v0
	v_add_f32_e32 v1, 1.0, v1
	v_rcp_f32_e32 v1, v1
	s_nop 0
	v_fma_f32 v1, v1, -2.0, 1.0
	v_add_f32_e32 v1, 1.0, v1
	v_mul_f32_e32 v0, v0, v1
	v_bfe_u32 v1, v0, 16, 1
	v_add3_u32 v2, v0, v1, s43
	v_or_b32_e32 v0, v22, v107
	v_lshlrev_b32_e32 v168, 1, v0
	v_lshl_add_u64 v[0:1], v[20:21], 0, v[168:169]
	global_store_short_d16_hi v[0:1], v2, off
	ds_read_b32 v0, v127
	s_waitcnt lgkmcnt(0)
	v_fmac_f32_e32 v3, v23, v0
	v_mul_f32_e32 v0, 0x3d372713, v3
	v_mul_f32_e32 v0, v3, v0
	v_fma_f32 v0, v3, v0, v3
	v_mul_f32_e32 v0, 0x3f4c422a, v0
	v_add_f32_e32 v0, v0, v0
	v_mul_f32_e32 v0, 0x3fb8aa3b, v0
	v_exp_f32_e32 v0, v0
	v_mul_f32_e32 v1, 0.5, v3
	v_add_f32_e32 v0, 1.0, v0
	v_rcp_f32_e32 v0, v0
	s_nop 0
	v_fma_f32 v0, v0, -2.0, 1.0
	v_add_f32_e32 v0, 1.0, v0
	v_mul_f32_e32 v0, v1, v0
	v_bfe_u32 v1, v0, 16, 1
	v_add3_u32 v2, v0, v1, s43
	v_or_b32_e32 v0, v22, v108
	v_lshlrev_b32_e32 v168, 1, v0
	v_lshl_add_u64 v[0:1], v[20:21], 0, v[168:169]
	global_store_short_d16_hi v[0:1], v2, off
	s_waitcnt lgkmcnt(0)
	s_andn2_b64 exec, exec, s[22:23]
	s_cbranch_execnz .LBB0_859
